# nt hint also on the P2 (Q/K/V-image/Z) and P5 (MZ) epilogue output stores, so GEMM operands stay in the last-level cache
# baseline (speedup 1.0000x reference)
.LBB0_191:
	s_sub_i32 s21, s29, 32
	s_cmp_lt_u32 s21, 16
	s_cbranch_scc1 .Lp2_vepi
	v_lshl_add_u32 v144, s28, 8, v146
	v_ashrrev_i32_e32 v145, 31, v144
	v_lshl_add_u64 v[154:155], v[144:145], 2, s[8:9]
	v_or_b32_e32 v156, 16, v144
	v_ashrrev_i32_e32 v157, 31, v156
	v_or_b32_e32 v160, 32, v144
	v_lshl_add_u64 v[158:159], v[156:157], 2, s[8:9]
	v_ashrrev_i32_e32 v161, 31, v160
	v_lshl_add_u64 v[162:163], v[160:161], 2, s[8:9]
	v_or_b32_e32 v158, 48, v144
	v_ashrrev_i32_e32 v159, 31, v158
	v_lshl_add_u64 v[162:163], v[158:159], 2, s[8:9]
	s_ashr_i32 s21, s29, 31
	s_lshr_b32 s21, s21, 28
	s_add_i32 s21, s29, s21
	s_add_i32 s23, s29, 15
	s_ashr_i32 s28, s21, 4
	s_cmp_lt_u32 s23, 31
	v_lshl_add_u32 v167, s29, 8, v148
	s_cselect_b64 vcc, -1, 0
	s_ashr_i32 s29, s28, 31
	s_lshl_b64 s[30:31], s[28:29], 27
	s_add_u32 s30, s42, s30
	s_addc_u32 s31, s43, s31
	s_lshl_b32 s21, s28, 12
	v_subrev_u32_e32 v154, s21, v167
	v_cndmask_b32_e32 v174, 1.0, v153, vcc
	v_ashrrev_i32_e32 v155, 31, v154
	v_lshlrev_b64 v[144:145], 13, v[144:145]
	v_lshl_add_u64 v[154:155], v[154:155], 1, s[30:31]
	v_lshl_add_u64 v[144:145], v[154:155], 0, v[144:145]
	v_lshlrev_b64 v[156:157], 13, v[156:157]
	v_lshl_add_u64 v[156:157], v[154:155], 0, v[156:157]
	v_lshlrev_b64 v[160:161], 13, v[160:161]
	v_lshl_add_u64 v[160:161], v[154:155], 0, v[160:161]
	s_waitcnt vmcnt(0)
	v_fmamk_f32 v162, v228, 0x39800000, v152
	v_rsq_f32_e32 v162, v162
	v_fmamk_f32 v163, v229, 0x39800000, v152
	v_fmamk_f32 v164, v230, 0x39800000, v152
	v_rsq_f32_e32 v166, v163
	v_rsq_f32_e32 v167, v164
	v_mul_f32_e32 v162, v174, v162
	v_pk_mul_f32 v[122:123], v[122:123], v[162:163] op_sel_hi:[1,0]
	v_mul_f32_e32 v166, v174, v166
	v_pk_mul_f32 v[126:127], v[126:127], v[162:163] op_sel_hi:[1,0]
	v_pk_mul_f32 v[124:125], v[124:125], v[162:163] op_sel_hi:[1,0]
	v_pk_mul_f32 v[120:121], v[120:121], v[162:163] op_sel_hi:[1,0]
	v_pk_mul_f32 v[110:111], v[110:111], v[162:163] op_sel_hi:[1,0]
	v_pk_mul_f32 v[108:109], v[108:109], v[162:163] op_sel_hi:[1,0]
	v_pk_mul_f32 v[164:165], v[102:103], v[162:163] op_sel_hi:[1,0]
	v_pk_mul_f32 v[162:163], v[100:101], v[162:163] op_sel_hi:[1,0]
	v_cvt_pk_bf16_f32 v100, v124, v125
	v_cvt_pk_bf16_f32 v101, v126, v127
	v_cvt_pk_bf16_f32 v102, v120, v121
	v_cvt_pk_bf16_f32 v103, v122, v123
	v_pk_mul_f32 v[122:123], v[88:89], v[166:167] op_sel_hi:[1,0]
	global_store_dwordx4 v[144:145], v[100:103], off nt
	v_cvt_pk_bf16_f32 v88, v108, v109
	v_cvt_pk_bf16_f32 v89, v110, v111
	v_pk_mul_f32 v[118:119], v[118:119], v[166:167] op_sel_hi:[1,0]
	v_pk_mul_f32 v[116:117], v[116:117], v[166:167] op_sel_hi:[1,0]
	v_pk_mul_f32 v[120:121], v[90:91], v[166:167] op_sel_hi:[1,0]
	v_cvt_pk_bf16_f32 v90, v162, v163
	v_cvt_pk_bf16_f32 v91, v164, v165
	global_store_dwordx4 v[144:145], v[88:91], off offset:256 nt
	v_mul_f32_e32 v168, v174, v167
	v_pk_mul_f32 v[114:115], v[114:115], v[166:167] op_sel_hi:[1,0]
	v_cvt_pk_bf16_f32 v88, v116, v117
	v_cvt_pk_bf16_f32 v89, v118, v119
	v_pk_mul_f32 v[112:113], v[112:113], v[166:167] op_sel_hi:[1,0]
	v_pk_mul_f32 v[94:95], v[94:95], v[166:167] op_sel_hi:[1,0]
	v_pk_mul_f32 v[92:93], v[92:93], v[166:167] op_sel_hi:[1,0]
	v_cvt_pk_bf16_f32 v90, v112, v113
	v_cvt_pk_bf16_f32 v91, v114, v115
	global_store_dwordx4 v[156:157], v[88:91], off nt
	v_pk_mul_f32 v[106:107], v[106:107], v[168:169] op_sel_hi:[1,0]
	v_pk_mul_f32 v[104:105], v[104:105], v[168:169] op_sel_hi:[1,0]
	v_cvt_pk_bf16_f32 v88, v92, v93
	v_cvt_pk_bf16_f32 v89, v94, v95
	v_cvt_pk_bf16_f32 v90, v122, v123
	v_cvt_pk_bf16_f32 v91, v120, v121
	global_store_dwordx4 v[156:157], v[88:91], off offset:256 nt
	v_pk_mul_f32 v[84:85], v[84:85], v[168:169] op_sel_hi:[1,0]
	v_pk_mul_f32 v[98:99], v[98:99], v[168:169] op_sel_hi:[1,0]
	v_cvt_pk_bf16_f32 v88, v104, v105
	v_cvt_pk_bf16_f32 v89, v106, v107
	v_pk_mul_f32 v[96:97], v[96:97], v[168:169] op_sel_hi:[1,0]
	v_pk_mul_f32 v[86:87], v[86:87], v[168:169] op_sel_hi:[1,0]
	v_cvt_pk_bf16_f32 v90, v96, v97
	v_cvt_pk_bf16_f32 v91, v98, v99
	global_store_dwordx4 v[160:161], v[88:91], off nt
	s_nop 1
	v_pk_mul_f32 v[88:89], v[82:83], v[168:169] op_sel_hi:[1,0]
	v_pk_mul_f32 v[82:83], v[80:81], v[168:169] op_sel_hi:[1,0]
	v_cvt_pk_bf16_f32 v80, v84, v85
	v_fmamk_f32 v84, v231, 0x39800000, v152
	v_rsq_f32_e32 v84, v84
	v_cvt_pk_bf16_f32 v81, v86, v87
	v_cvt_pk_bf16_f32 v82, v82, v83
	v_cvt_pk_bf16_f32 v83, v88, v89
	global_store_dwordx4 v[160:161], v[80:83], off offset:256 nt
	s_nop 1
	v_mul_f32_e32 v80, v174, v84
	v_lshlrev_b64 v[82:83], 13, v[158:159]
	v_lshl_add_u64 v[82:83], v[154:155], 0, v[82:83]
	v_pk_mul_f32 v[78:79], v[78:79], v[80:81] op_sel_hi:[1,0]
	v_pk_mul_f32 v[76:77], v[76:77], v[80:81] op_sel_hi:[1,0]
	v_pk_mul_f32 v[84:85], v[74:75], v[80:81] op_sel_hi:[1,0]
	v_pk_mul_f32 v[74:75], v[72:73], v[80:81] op_sel_hi:[1,0]
	v_cvt_pk_bf16_f32 v72, v76, v77
	v_cvt_pk_bf16_f32 v73, v78, v79
	v_pk_mul_f32 v[68:69], v[68:69], v[80:81] op_sel_hi:[1,0]
	v_cvt_pk_bf16_f32 v74, v74, v75
	v_cvt_pk_bf16_f32 v75, v84, v85
	global_store_dwordx4 v[82:83], v[72:75], off nt
	v_pk_mul_f32 v[70:71], v[70:71], v[80:81] op_sel_hi:[1,0]
	s_nop 0
	v_pk_mul_f32 v[72:73], v[66:67], v[80:81] op_sel_hi:[1,0]
	v_pk_mul_f32 v[66:67], v[64:65], v[80:81] op_sel_hi:[1,0]
	v_cvt_pk_bf16_f32 v64, v68, v69
	v_fmamk_f32 v68, v232, 0x39800000, v152
	v_rsq_f32_e32 v68, v68
	v_cvt_pk_bf16_f32 v65, v70, v71
	v_cvt_pk_bf16_f32 v66, v66, v67
	v_cvt_pk_bf16_f32 v67, v72, v73
	global_store_dwordx4 v[82:83], v[64:67], off offset:256 nt
	s_nop 1
	v_mul_f32_e32 v64, v174, v68
	v_pk_mul_f32 v[60:61], v[60:61], v[64:65] op_sel_hi:[1,0]
	v_pk_mul_f32 v[68:69], v[58:59], v[64:65] op_sel_hi:[1,0]
	v_pk_mul_f32 v[58:59], v[56:57], v[64:65] op_sel_hi:[1,0]
	v_cvt_pk_bf16_f32 v56, v60, v61
	v_add_co_u32_e32 v60, vcc, s69, v144
	v_pk_mul_f32 v[62:63], v[62:63], v[64:65] op_sel_hi:[1,0]
	s_nop 0
	v_addc_co_u32_e32 v61, vcc, 0, v145, vcc
	v_cvt_pk_bf16_f32 v57, v62, v63
	v_pk_mul_f32 v[52:53], v[52:53], v[64:65] op_sel_hi:[1,0]
	v_cvt_pk_bf16_f32 v58, v58, v59
	v_cvt_pk_bf16_f32 v59, v68, v69
	global_store_dwordx4 v[60:61], v[56:59], off nt
	v_lshl_add_u64 v[66:67], v[144:145], 0, s[4:5]
	v_pk_mul_f32 v[54:55], v[54:55], v[64:65] op_sel_hi:[1,0]
	v_pk_mul_f32 v[56:57], v[50:51], v[64:65] op_sel_hi:[1,0]
	v_pk_mul_f32 v[50:51], v[48:49], v[64:65] op_sel_hi:[1,0]
	v_cvt_pk_bf16_f32 v48, v52, v53
	v_fmamk_f32 v52, v233, 0x39800000, v152
	v_rsq_f32_e32 v52, v52
	v_cvt_pk_bf16_f32 v49, v54, v55
	v_cvt_pk_bf16_f32 v50, v50, v51
	v_cvt_pk_bf16_f32 v51, v56, v57
	global_store_dwordx4 v[66:67], v[48:51], off offset:256 nt
	s_nop 1
	v_mul_f32_e32 v48, v174, v52
	v_pk_mul_f32 v[44:45], v[44:45], v[48:49] op_sel_hi:[1,0]
	v_pk_mul_f32 v[52:53], v[42:43], v[48:49] op_sel_hi:[1,0]
	v_pk_mul_f32 v[42:43], v[40:41], v[48:49] op_sel_hi:[1,0]
	v_cvt_pk_bf16_f32 v40, v44, v45
	v_add_co_u32_e32 v44, vcc, s70, v144
	v_pk_mul_f32 v[46:47], v[46:47], v[48:49] op_sel_hi:[1,0]
	s_nop 0
	v_addc_co_u32_e32 v45, vcc, 0, v145, vcc
	v_cvt_pk_bf16_f32 v41, v46, v47
	v_pk_mul_f32 v[36:37], v[36:37], v[48:49] op_sel_hi:[1,0]
	v_cvt_pk_bf16_f32 v42, v42, v43
	v_cvt_pk_bf16_f32 v43, v52, v53
	global_store_dwordx4 v[44:45], v[40:43], off nt
	v_lshl_add_u64 v[50:51], v[144:145], 0, s[14:15]
	v_pk_mul_f32 v[38:39], v[38:39], v[48:49] op_sel_hi:[1,0]
	v_pk_mul_f32 v[40:41], v[34:35], v[48:49] op_sel_hi:[1,0]
	v_pk_mul_f32 v[34:35], v[32:33], v[48:49] op_sel_hi:[1,0]
	v_cvt_pk_bf16_f32 v32, v36, v37
	v_fmamk_f32 v36, v234, 0x39800000, v152
	v_rsq_f32_e32 v36, v36
	v_cvt_pk_bf16_f32 v33, v38, v39
	v_cvt_pk_bf16_f32 v34, v34, v35
	v_cvt_pk_bf16_f32 v35, v40, v41
	global_store_dwordx4 v[50:51], v[32:35], off offset:256 nt
	s_nop 1
	v_mul_f32_e32 v32, v174, v36
	v_pk_mul_f32 v[28:29], v[28:29], v[32:33] op_sel_hi:[1,0]
	v_pk_mul_f32 v[36:37], v[26:27], v[32:33] op_sel_hi:[1,0]
	v_pk_mul_f32 v[26:27], v[24:25], v[32:33] op_sel_hi:[1,0]
	v_cvt_pk_bf16_f32 v24, v28, v29
	v_add_co_u32_e32 v28, vcc, s71, v144
	v_pk_mul_f32 v[30:31], v[30:31], v[32:33] op_sel_hi:[1,0]
	s_nop 0
	v_addc_co_u32_e32 v29, vcc, 0, v145, vcc
	v_cvt_pk_bf16_f32 v25, v30, v31
	v_pk_mul_f32 v[20:21], v[20:21], v[32:33] op_sel_hi:[1,0]
	v_cvt_pk_bf16_f32 v26, v26, v27
	v_cvt_pk_bf16_f32 v27, v36, v37
	global_store_dwordx4 v[28:29], v[24:27], off nt
	v_lshl_add_u64 v[34:35], v[144:145], 0, s[16:17]
	v_pk_mul_f32 v[22:23], v[22:23], v[32:33] op_sel_hi:[1,0]
	v_pk_mul_f32 v[24:25], v[18:19], v[32:33] op_sel_hi:[1,0]
	v_pk_mul_f32 v[18:19], v[16:17], v[32:33] op_sel_hi:[1,0]
	v_cvt_pk_bf16_f32 v16, v20, v21
	v_fmamk_f32 v20, v235, 0x39800000, v152
	v_rsq_f32_e32 v20, v20
	v_cvt_pk_bf16_f32 v17, v22, v23
	v_cvt_pk_bf16_f32 v18, v18, v19
	v_cvt_pk_bf16_f32 v19, v24, v25
	global_store_dwordx4 v[34:35], v[16:19], off offset:256 nt
	s_nop 1
	v_mul_f32_e32 v16, v174, v20
	v_pk_mul_f32 v[12:13], v[12:13], v[16:17] op_sel_hi:[1,0]
	v_pk_mul_f32 v[20:21], v[10:11], v[16:17] op_sel_hi:[1,0]
	v_pk_mul_f32 v[10:11], v[8:9], v[16:17] op_sel_hi:[1,0]
	v_cvt_pk_bf16_f32 v8, v12, v13
	v_add_co_u32_e32 v12, vcc, s72, v144
	v_pk_mul_f32 v[14:15], v[14:15], v[16:17] op_sel_hi:[1,0]
	s_nop 0
	v_addc_co_u32_e32 v13, vcc, 0, v145, vcc
	v_cvt_pk_bf16_f32 v9, v14, v15
	v_lshl_add_u64 v[18:19], v[144:145], 0, s[18:19]
	v_cvt_pk_bf16_f32 v10, v10, v11
	v_cvt_pk_bf16_f32 v11, v20, v21
	global_store_dwordx4 v[12:13], v[8:11], off nt
	s_andn2_b64 vcc, exec, s[0:1]
	s_mov_b64 s[0:1], -1
	v_pk_mul_f32 v[8:9], v[2:3], v[16:17] op_sel_hi:[1,0]
	v_pk_mul_f32 v[2:3], v[0:1], v[16:17] op_sel_hi:[1,0]
	v_pk_mul_f32 v[6:7], v[6:7], v[16:17] op_sel_hi:[1,0]
	v_pk_mul_f32 v[4:5], v[4:5], v[16:17] op_sel_hi:[1,0]
	s_nop 0
	v_cvt_pk_bf16_f32 v0, v4, v5
	v_cvt_pk_bf16_f32 v1, v6, v7
	v_cvt_pk_bf16_f32 v2, v2, v3
	v_cvt_pk_bf16_f32 v3, v8, v9
	global_store_dwordx4 v[18:19], v[0:3], off offset:256 nt
	s_cbranch_vccnz .LBB0_180

.Lp2_vepi:
	v_mbcnt_lo_u32_b32 v144, -1, 0
	v_mbcnt_hi_u32_b32 v144, -1, v144
	s_and_b32 s21, s89, 3
	s_lshr_b32 s23, s89, 2
	v_and_b32_e32 v145, 15, v144
	v_lshrrev_b32_e32 v154, 4, v144
	s_lshl_b32 s30, s28, 8
	s_lshl_b32 s31, s21, 5
	s_add_i32 s30, s30, s31
	v_lshl_add_u32 v155, v154, 3, s30
	v_lshlrev_b32_e32 v155, 2, v155
	global_load_dwordx4 v[226:229], v155, s[8:9]
	global_load_dwordx4 v[230:233], v155, s[8:9] offset:16
	global_load_dwordx4 v[234:237], v155, s[8:9] offset:512
	global_load_dwordx4 v[238:241], v155, s[8:9] offset:528
	s_sub_i32 s30, s29, 32
	s_lshl_b32 s30, s30, 8
	s_lshl_b32 s31, s28, 2
	s_add_i32 s30, s30, s31
	s_lshr_b32 s31, s21, 1
	s_add_i32 s30, s30, s31
	s_lshl_b32 s30, s30, 15
	s_add_u32 s30, s30, 0x20200000
	s_addc_u32 s31, 0, 0
	s_add_u32 s30, s66, s30
	s_addc_u32 s31, s67, s31
	s_and_b32 s21, s21, 1
	s_lshl_b32 s21, s21, 2
	v_and_b32_e32 v156, 1, v154
	v_lshlrev_b32_e32 v156, 1, v156
	v_or_b32_e32 v156, s21, v156
	v_bfe_u32 v157, v144, 1, 3
	v_xor_b32_e32 v156, v156, v157
	v_lshlrev_b32_e32 v156, 4, v156
	v_lshrrev_b32_e32 v157, 1, v154
	v_lshl_add_u32 v156, v157, 3, v156
	v_lshl_add_u32 v156, v145, 7, v156
	s_lshl_b32 s23, s23, 13
	v_add_u32_e32 v156, s23, v156
	s_waitcnt vmcnt(0)
	v_fmamk_f32 v226, v226, 0x39800000, v152
	v_fmamk_f32 v227, v227, 0x39800000, v152
	v_fmamk_f32 v228, v228, 0x39800000, v152
	v_fmamk_f32 v229, v229, 0x39800000, v152
	v_fmamk_f32 v230, v230, 0x39800000, v152
	v_fmamk_f32 v231, v231, 0x39800000, v152
	v_fmamk_f32 v232, v232, 0x39800000, v152
	v_fmamk_f32 v233, v233, 0x39800000, v152
	v_fmamk_f32 v234, v234, 0x39800000, v152
	v_fmamk_f32 v235, v235, 0x39800000, v152
	v_fmamk_f32 v236, v236, 0x39800000, v152
	v_fmamk_f32 v237, v237, 0x39800000, v152
	v_fmamk_f32 v238, v238, 0x39800000, v152
	v_fmamk_f32 v239, v239, 0x39800000, v152
	v_fmamk_f32 v240, v240, 0x39800000, v152
	v_fmamk_f32 v241, v241, 0x39800000, v152
	v_rsq_f32_e32 v226, v226
	v_rsq_f32_e32 v227, v227
	v_rsq_f32_e32 v228, v228
	v_rsq_f32_e32 v229, v229
	v_rsq_f32_e32 v230, v230
	v_rsq_f32_e32 v231, v231
	v_rsq_f32_e32 v232, v232
	v_rsq_f32_e32 v233, v233
	v_rsq_f32_e32 v234, v234
	v_rsq_f32_e32 v235, v235
	v_rsq_f32_e32 v236, v236
	v_rsq_f32_e32 v237, v237
	v_rsq_f32_e32 v238, v238
	v_rsq_f32_e32 v239, v239
	v_rsq_f32_e32 v240, v240
	v_rsq_f32_e32 v241, v241
	s_nop 0
	v_mul_f32_e32 v124, v124, v226
	v_mul_f32_e32 v125, v125, v227
	v_mul_f32_e32 v126, v126, v228
	v_mul_f32_e32 v127, v127, v229
	v_mul_f32_e32 v120, v120, v230
	v_mul_f32_e32 v121, v121, v231
	v_mul_f32_e32 v122, v122, v232
	v_mul_f32_e32 v123, v123, v233
	v_cvt_pk_bf16_f32 v124, v124, v125
	v_cvt_pk_bf16_f32 v125, v126, v127
	v_cvt_pk_bf16_f32 v120, v120, v121
	v_cvt_pk_bf16_f32 v121, v122, v123
	v_mov_b32_e32 v157, v156
	v_xor_b32_e32 v158, 16, v157
	global_store_dwordx2 v157, v[124:125], s[30:31] nt
	global_store_dwordx2 v158, v[120:121], s[30:31] nt
	v_mul_f32_e32 v108, v108, v234
	v_mul_f32_e32 v109, v109, v235
	v_mul_f32_e32 v110, v110, v236
	v_mul_f32_e32 v111, v111, v237
	v_mul_f32_e32 v100, v100, v238
	v_mul_f32_e32 v101, v101, v239
	v_mul_f32_e32 v102, v102, v240
	v_mul_f32_e32 v103, v103, v241
	v_cvt_pk_bf16_f32 v108, v108, v109
	v_cvt_pk_bf16_f32 v109, v110, v111
	v_cvt_pk_bf16_f32 v100, v100, v101
	v_cvt_pk_bf16_f32 v101, v102, v103
	v_add_u32_e32 v157, 0x10000, v156
	v_xor_b32_e32 v158, 16, v157
	global_store_dwordx2 v157, v[108:109], s[30:31] nt
	global_store_dwordx2 v158, v[100:101], s[30:31] nt
	v_mul_f32_e32 v116, v116, v226
	v_mul_f32_e32 v117, v117, v227
	v_mul_f32_e32 v118, v118, v228
	v_mul_f32_e32 v119, v119, v229
	v_mul_f32_e32 v112, v112, v230
	v_mul_f32_e32 v113, v113, v231
	v_mul_f32_e32 v114, v114, v232
	v_mul_f32_e32 v115, v115, v233
	v_cvt_pk_bf16_f32 v116, v116, v117
	v_cvt_pk_bf16_f32 v117, v118, v119
	v_cvt_pk_bf16_f32 v112, v112, v113
	v_cvt_pk_bf16_f32 v113, v114, v115
	v_add_u32_e32 v157, 0x800, v156
	v_xor_b32_e32 v158, 16, v157
	global_store_dwordx2 v157, v[116:117], s[30:31] nt
	global_store_dwordx2 v158, v[112:113], s[30:31] nt
	v_mul_f32_e32 v92, v92, v234
	v_mul_f32_e32 v93, v93, v235
	v_mul_f32_e32 v94, v94, v236
	v_mul_f32_e32 v95, v95, v237
	v_mul_f32_e32 v88, v88, v238
	v_mul_f32_e32 v89, v89, v239
	v_mul_f32_e32 v90, v90, v240
	v_mul_f32_e32 v91, v91, v241
	v_cvt_pk_bf16_f32 v92, v92, v93
	v_cvt_pk_bf16_f32 v93, v94, v95
	v_cvt_pk_bf16_f32 v88, v88, v89
	v_cvt_pk_bf16_f32 v89, v90, v91
	v_add_u32_e32 v157, 0x10800, v156
	v_xor_b32_e32 v158, 16, v157
	global_store_dwordx2 v157, v[92:93], s[30:31] nt
	global_store_dwordx2 v158, v[88:89], s[30:31] nt
	v_mul_f32_e32 v104, v104, v226
	v_mul_f32_e32 v105, v105, v227
	v_mul_f32_e32 v106, v106, v228
	v_mul_f32_e32 v107, v107, v229
	v_mul_f32_e32 v96, v96, v230
	v_mul_f32_e32 v97, v97, v231
	v_mul_f32_e32 v98, v98, v232
	v_mul_f32_e32 v99, v99, v233
	v_cvt_pk_bf16_f32 v104, v104, v105
	v_cvt_pk_bf16_f32 v105, v106, v107
	v_cvt_pk_bf16_f32 v96, v96, v97
	v_cvt_pk_bf16_f32 v97, v98, v99
	v_add_u32_e32 v157, 0x1000, v156
	v_xor_b32_e32 v158, 16, v157
	global_store_dwordx2 v157, v[104:105], s[30:31] nt
	global_store_dwordx2 v158, v[96:97], s[30:31] nt
	v_mul_f32_e32 v84, v84, v234
	v_mul_f32_e32 v85, v85, v235
	v_mul_f32_e32 v86, v86, v236
	v_mul_f32_e32 v87, v87, v237
	v_mul_f32_e32 v80, v80, v238
	v_mul_f32_e32 v81, v81, v239
	v_mul_f32_e32 v82, v82, v240
	v_mul_f32_e32 v83, v83, v241
	v_cvt_pk_bf16_f32 v84, v84, v85
	v_cvt_pk_bf16_f32 v85, v86, v87
	v_cvt_pk_bf16_f32 v80, v80, v81
	v_cvt_pk_bf16_f32 v81, v82, v83
	v_add_u32_e32 v157, 0x11000, v156
	v_xor_b32_e32 v158, 16, v157
	global_store_dwordx2 v157, v[84:85], s[30:31] nt
	global_store_dwordx2 v158, v[80:81], s[30:31] nt
	v_mul_f32_e32 v76, v76, v226
	v_mul_f32_e32 v77, v77, v227
	v_mul_f32_e32 v78, v78, v228
	v_mul_f32_e32 v79, v79, v229
	v_mul_f32_e32 v72, v72, v230
	v_mul_f32_e32 v73, v73, v231
	v_mul_f32_e32 v74, v74, v232
	v_mul_f32_e32 v75, v75, v233
	v_cvt_pk_bf16_f32 v76, v76, v77
	v_cvt_pk_bf16_f32 v77, v78, v79
	v_cvt_pk_bf16_f32 v72, v72, v73
	v_cvt_pk_bf16_f32 v73, v74, v75
	v_add_u32_e32 v157, 0x1800, v156
	v_xor_b32_e32 v158, 16, v157
	global_store_dwordx2 v157, v[76:77], s[30:31] nt
	global_store_dwordx2 v158, v[72:73], s[30:31] nt
	v_mul_f32_e32 v68, v68, v234
	v_mul_f32_e32 v69, v69, v235
	v_mul_f32_e32 v70, v70, v236
	v_mul_f32_e32 v71, v71, v237
	v_mul_f32_e32 v64, v64, v238
	v_mul_f32_e32 v65, v65, v239
	v_mul_f32_e32 v66, v66, v240
	v_mul_f32_e32 v67, v67, v241
	v_cvt_pk_bf16_f32 v68, v68, v69
	v_cvt_pk_bf16_f32 v69, v70, v71
	v_cvt_pk_bf16_f32 v64, v64, v65
	v_cvt_pk_bf16_f32 v65, v66, v67
	v_add_u32_e32 v157, 0x11800, v156
	v_xor_b32_e32 v158, 16, v157
	global_store_dwordx2 v157, v[68:69], s[30:31] nt
	global_store_dwordx2 v158, v[64:65], s[30:31] nt
	v_mul_f32_e32 v60, v60, v226
	v_mul_f32_e32 v61, v61, v227
	v_mul_f32_e32 v62, v62, v228
	v_mul_f32_e32 v63, v63, v229
	v_mul_f32_e32 v56, v56, v230
	v_mul_f32_e32 v57, v57, v231
	v_mul_f32_e32 v58, v58, v232
	v_mul_f32_e32 v59, v59, v233
	v_cvt_pk_bf16_f32 v60, v60, v61
	v_cvt_pk_bf16_f32 v61, v62, v63
	v_cvt_pk_bf16_f32 v56, v56, v57
	v_cvt_pk_bf16_f32 v57, v58, v59
	v_add_u32_e32 v157, 0x4000, v156
	v_xor_b32_e32 v158, 16, v157
	global_store_dwordx2 v157, v[60:61], s[30:31] nt
	global_store_dwordx2 v158, v[56:57], s[30:31] nt
	v_mul_f32_e32 v52, v52, v234
	v_mul_f32_e32 v53, v53, v235
	v_mul_f32_e32 v54, v54, v236
	v_mul_f32_e32 v55, v55, v237
	v_mul_f32_e32 v48, v48, v238
	v_mul_f32_e32 v49, v49, v239
	v_mul_f32_e32 v50, v50, v240
	v_mul_f32_e32 v51, v51, v241
	v_cvt_pk_bf16_f32 v52, v52, v53
	v_cvt_pk_bf16_f32 v53, v54, v55
	v_cvt_pk_bf16_f32 v48, v48, v49
	v_cvt_pk_bf16_f32 v49, v50, v51
	v_add_u32_e32 v157, 0x14000, v156
	v_xor_b32_e32 v158, 16, v157
	global_store_dwordx2 v157, v[52:53], s[30:31] nt
	global_store_dwordx2 v158, v[48:49], s[30:31] nt
	v_mul_f32_e32 v44, v44, v226
	v_mul_f32_e32 v45, v45, v227
	v_mul_f32_e32 v46, v46, v228
	v_mul_f32_e32 v47, v47, v229
	v_mul_f32_e32 v40, v40, v230
	v_mul_f32_e32 v41, v41, v231
	v_mul_f32_e32 v42, v42, v232
	v_mul_f32_e32 v43, v43, v233
	v_cvt_pk_bf16_f32 v44, v44, v45
	v_cvt_pk_bf16_f32 v45, v46, v47
	v_cvt_pk_bf16_f32 v40, v40, v41
	v_cvt_pk_bf16_f32 v41, v42, v43
	v_add_u32_e32 v157, 0x4800, v156
	v_xor_b32_e32 v158, 16, v157
	global_store_dwordx2 v157, v[44:45], s[30:31] nt
	global_store_dwordx2 v158, v[40:41], s[30:31] nt
	v_mul_f32_e32 v36, v36, v234
	v_mul_f32_e32 v37, v37, v235
	v_mul_f32_e32 v38, v38, v236
	v_mul_f32_e32 v39, v39, v237
	v_mul_f32_e32 v32, v32, v238
	v_mul_f32_e32 v33, v33, v239
	v_mul_f32_e32 v34, v34, v240
	v_mul_f32_e32 v35, v35, v241
	v_cvt_pk_bf16_f32 v36, v36, v37
	v_cvt_pk_bf16_f32 v37, v38, v39
	v_cvt_pk_bf16_f32 v32, v32, v33
	v_cvt_pk_bf16_f32 v33, v34, v35
	v_add_u32_e32 v157, 0x14800, v156
	v_xor_b32_e32 v158, 16, v157
	global_store_dwordx2 v157, v[36:37], s[30:31] nt
	global_store_dwordx2 v158, v[32:33], s[30:31] nt
	v_mul_f32_e32 v28, v28, v226
	v_mul_f32_e32 v29, v29, v227
	v_mul_f32_e32 v30, v30, v228
	v_mul_f32_e32 v31, v31, v229
	v_mul_f32_e32 v24, v24, v230
	v_mul_f32_e32 v25, v25, v231
	v_mul_f32_e32 v26, v26, v232
	v_mul_f32_e32 v27, v27, v233
	v_cvt_pk_bf16_f32 v28, v28, v29
	v_cvt_pk_bf16_f32 v29, v30, v31
	v_cvt_pk_bf16_f32 v24, v24, v25
	v_cvt_pk_bf16_f32 v25, v26, v27
	v_add_u32_e32 v157, 0x5000, v156
	v_xor_b32_e32 v158, 16, v157
	global_store_dwordx2 v157, v[28:29], s[30:31] nt
	global_store_dwordx2 v158, v[24:25], s[30:31] nt
	v_mul_f32_e32 v20, v20, v234
	v_mul_f32_e32 v21, v21, v235
	v_mul_f32_e32 v22, v22, v236
	v_mul_f32_e32 v23, v23, v237
	v_mul_f32_e32 v16, v16, v238
	v_mul_f32_e32 v17, v17, v239
	v_mul_f32_e32 v18, v18, v240
	v_mul_f32_e32 v19, v19, v241
	v_cvt_pk_bf16_f32 v20, v20, v21
	v_cvt_pk_bf16_f32 v21, v22, v23
	v_cvt_pk_bf16_f32 v16, v16, v17
	v_cvt_pk_bf16_f32 v17, v18, v19
	v_add_u32_e32 v157, 0x15000, v156
	v_xor_b32_e32 v158, 16, v157
	global_store_dwordx2 v157, v[20:21], s[30:31] nt
	global_store_dwordx2 v158, v[16:17], s[30:31] nt
	v_mul_f32_e32 v12, v12, v226
	v_mul_f32_e32 v13, v13, v227
	v_mul_f32_e32 v14, v14, v228
	v_mul_f32_e32 v15, v15, v229
	v_mul_f32_e32 v8, v8, v230
	v_mul_f32_e32 v9, v9, v231
	v_mul_f32_e32 v10, v10, v232
	v_mul_f32_e32 v11, v11, v233
	v_cvt_pk_bf16_f32 v12, v12, v13
	v_cvt_pk_bf16_f32 v13, v14, v15
	v_cvt_pk_bf16_f32 v8, v8, v9
	v_cvt_pk_bf16_f32 v9, v10, v11
	v_add_u32_e32 v157, 0x5800, v156
	v_xor_b32_e32 v158, 16, v157
	global_store_dwordx2 v157, v[12:13], s[30:31] nt
	global_store_dwordx2 v158, v[8:9], s[30:31] nt
	v_mul_f32_e32 v4, v4, v234
	v_mul_f32_e32 v5, v5, v235
	v_mul_f32_e32 v6, v6, v236
	v_mul_f32_e32 v7, v7, v237
	v_mul_f32_e32 v0, v0, v238
	v_mul_f32_e32 v1, v1, v239
	v_mul_f32_e32 v2, v2, v240
	v_mul_f32_e32 v3, v3, v241
	v_cvt_pk_bf16_f32 v4, v4, v5
	v_cvt_pk_bf16_f32 v5, v6, v7
	v_cvt_pk_bf16_f32 v0, v0, v1
	v_cvt_pk_bf16_f32 v1, v2, v3
	v_add_u32_e32 v157, 0x15800, v156
	v_xor_b32_e32 v158, 16, v157
	global_store_dwordx2 v157, v[4:5], s[30:31] nt
	global_store_dwordx2 v158, v[0:1], s[30:31] nt
	s_andn2_b64 vcc, exec, s[0:1]
	s_mov_b64 s[0:1], -1
	s_cbranch_vccnz .LBB0_180
	s_branch .Lp2_join

.LBB0_556:
	s_ashr_i32 s57, s56, 31
	v_mov_b32_e32 v1, v0
	s_lshl_b64 s[56:57], s[56:57], 18
	s_andn2_b64 vcc, exec, s[58:59]
	v_mov_b32_e32 v123, v122
	s_cbranch_vccnz .LBB0_558
	v_mov_b32_e32 v60, v0
	v_mov_b32_e32 v61, v0
	v_mov_b32_e32 v62, v130
	v_mov_b32_e32 v63, v131
	s_waitcnt lgkmcnt(1)
	v_mov_b32_e32 v82, v0
	v_mov_b32_e32 v83, v0
	v_mov_b32_e32 v84, v126
	v_mov_b32_e32 v85, v127
	v_mfma_f32_16x16x32_bf16 v[60:63], v[60:63], v[0:3], 0
	v_mov_b32_e32 v88, v122
	v_mov_b32_e32 v89, v122
	v_lshl_add_u64 v[64:65], v[150:151], 0, s[56:57]
	v_mfma_f32_16x16x32_bf16 v[82:85], v[82:85], v[0:3], 0
	v_lshl_add_u64 v[64:65], v[164:165], 1, v[64:65]
	s_nop 2
	v_pk_add_f32 v[62:63], v[88:89], v[62:63]
	v_pk_add_f32 v[60:61], v[122:123], v[60:61]
	s_nop 0
	v_cvt_pk_bf16_f32 v60, v60, v61
	s_nop 0
	v_pk_add_f32 v[84:85], v[88:89], v[84:85]
	v_pk_add_f32 v[82:83], v[122:123], v[82:83]
	v_cvt_pk_bf16_f32 v61, v62, v63
	s_nop 0
	v_cvt_pk_bf16_f32 v62, v82, v83
	v_cvt_pk_bf16_f32 v63, v84, v85
	global_store_dwordx4 v[64:65], v[60:63], off nt
	v_mov_b32_e32 v64, v138
	v_mov_b32_e32 v65, v134
	v_cvt_pk_bf16_f32 v60, v78, v79
	v_cvt_pk_bf16_f32 v61, v70, v71
	v_cvt_pk_bf16_f32 v62, v74, v75
	v_cvt_pk_bf16_f32 v63, v66, v67
	v_mov_b32_e32 v134, v139
	v_mov_b32_e32 v66, v140
	v_mov_b32_e32 v67, v136
	v_mov_b32_e32 v136, v141
	v_pk_mul_f32 v[64:65], v[64:65], s[38:39] op_sel_hi:[1,0]
	v_pk_mul_f32 v[120:121], v[134:135], s[38:39] op_sel_hi:[1,0]
	v_pk_mul_f32 v[124:125], v[66:67], s[38:39] op_sel_hi:[1,0]
	v_pk_mul_f32 v[174:175], v[136:137], s[38:39] op_sel_hi:[1,0]
.LBB0_558:
	v_lshlrev_b64 v[66:67], 14, v[178:179]
	v_lshl_add_u64 v[70:71], s[48:49], 0, v[66:67]
	v_lshlrev_b64 v[66:67], 1, v[164:165]
	v_lshl_add_u64 v[70:71], v[70:71], 0, v[66:67]
	global_store_dwordx4 v[70:71], v[60:63], off nt
	v_mov_b32_e32 v112, v132
	v_mov_b32_e32 v113, v133
	v_mul_f32_e32 v62, 0x3fb8aa3b, v211
	v_pk_mul_f32 v[70:71], v[56:57], v[62:63] op_sel_hi:[1,0]
	v_lshlrev_b64 v[60:61], 14, v[180:181]
	v_exp_f32_e64 v63, -v70
	v_lshl_add_u64 v[60:61], s[48:49], 0, v[60:61]
	v_lshl_add_u64 v[60:61], v[60:61], 0, v[66:67]
	v_mov_b32_e32 v108, v128
	v_pk_mul_f32 v[78:79], v[52:53], v[62:63] op_sel_hi:[1,0]
	v_add_f32_e32 v52, 1.0, v63
	s_waitcnt lgkmcnt(1)
	v_rcp_f32_e32 v82, v52
	v_exp_f32_e64 v83, -v78
	v_pk_mul_f32 v[74:75], v[58:59], v[62:63] op_sel_hi:[1,0]
	v_mfma_f32_16x16x32_bf16 v[56:59], v[130:133], v[92:95], 0
	v_mul_f32_e32 v70, v70, v82
	v_add_f32_e32 v82, 1.0, v83
	v_rcp_f32_e32 v82, v82
	v_exp_f32_e64 v83, -v71
	v_mul_f32_e32 v70, v70, v65
	s_nop 2
	v_mul_f32_e32 v56, v70, v56
	v_mul_f32_e32 v70, v78, v82
	v_add_f32_e32 v78, 1.0, v83
	v_pk_mul_f32 v[62:63], v[54:55], v[62:63] op_sel_hi:[1,0]
	v_mfma_f32_16x16x32_bf16 v[52:55], v[126:129], v[92:95], 0
	v_rcp_f32_e32 v78, v78
	v_exp_f32_e64 v82, -v79
	v_mul_f32_e32 v70, v70, v64
	v_mov_b32_e32 v109, v129
	v_mov_b32_e32 v104, v114
	s_nop 2
	v_mul_f32_e32 v70, v70, v52
	v_mul_f32_e32 v52, v71, v78
	v_add_f32_e32 v71, 1.0, v82
	v_rcp_f32_e32 v71, v71
	v_exp_f32_e64 v78, -v74
	v_mul_f32_e32 v52, v52, v121
	v_mul_f32_e32 v52, v52, v57
	v_mul_f32_e32 v57, v79, v71
	v_add_f32_e32 v71, 1.0, v78
	v_rcp_f32_e32 v71, v71
	v_exp_f32_e64 v78, -v62
	v_mul_f32_e32 v57, v57, v120
	v_mul_f32_e32 v57, v57, v53
	v_mul_f32_e32 v53, v74, v71
	v_add_f32_e32 v71, 1.0, v78
	v_rcp_f32_e32 v71, v71
	v_mul_f32_e32 v53, v53, v125
	v_mul_f32_e32 v53, v53, v58
	v_exp_f32_e64 v58, -v75
	v_mul_f32_e32 v62, v62, v71
	v_exp_f32_e64 v71, -v63
	v_mul_f32_e32 v62, v62, v124
	v_add_f32_e32 v58, 1.0, v58
	v_mul_f32_e32 v62, v62, v54
	v_add_f32_e32 v54, 1.0, v71
	v_rcp_f32_e32 v58, v58
	v_rcp_f32_e32 v54, v54
	v_cvt_pk_bf16_f32 v52, v56, v52
	v_mov_b32_e32 v105, v115
	v_mul_f32_e32 v58, v75, v58
	v_mul_f32_e32 v54, v63, v54
	v_mul_f32_e32 v58, v58, v175
	v_mul_f32_e32 v54, v54, v174
	v_mul_f32_e32 v58, v58, v59
	v_mul_f32_e32 v55, v54, v55
	v_cvt_pk_bf16_f32 v53, v53, v58
	v_cvt_pk_bf16_f32 v54, v70, v57
	v_cvt_pk_bf16_f32 v55, v62, v55
	global_store_dwordx4 v[60:61], v[52:55], off nt
	v_mov_b32_e32 v88, v102
	v_mov_b32_e32 v89, v103
	v_mul_f32_e32 v54, 0x3fb8aa3b, v210
	v_pk_mul_f32 v[58:59], v[48:49], v[54:55] op_sel_hi:[1,0]
	v_pk_mul_f32 v[60:61], v[44:45], v[54:55] op_sel_hi:[1,0]
	v_exp_f32_e64 v44, -v58
	v_exp_f32_e64 v63, -v60
	v_pk_mul_f32 v[56:57], v[50:51], v[54:55] op_sel_hi:[1,0]
	v_mfma_f32_16x16x32_bf16 v[48:51], v[112:115], v[92:95], 0
	v_add_f32_e32 v44, 1.0, v44
	v_rcp_f32_e32 v62, v44
	v_pk_mul_f32 v[54:55], v[46:47], v[54:55] op_sel_hi:[1,0]
	v_mfma_f32_16x16x32_bf16 v[44:47], v[108:111], v[92:95], 0
	v_lshlrev_b64 v[52:53], 14, v[176:177]
	v_mul_f32_e32 v58, v58, v62
	v_add_f32_e32 v62, 1.0, v63
	v_rcp_f32_e32 v62, v62
	v_exp_f32_e64 v63, -v59
	v_mul_f32_e32 v58, v58, v65
	v_mul_f32_e32 v48, v58, v48
	v_mul_f32_e32 v58, v60, v62
	v_add_f32_e32 v60, 1.0, v63
	v_rcp_f32_e32 v60, v60
	v_exp_f32_e64 v62, -v61
	v_mul_f32_e32 v58, v58, v64
	v_mul_f32_e32 v58, v58, v44
	v_mul_f32_e32 v44, v59, v60
	v_add_f32_e32 v59, 1.0, v62
	v_rcp_f32_e32 v59, v59
	v_exp_f32_e64 v60, -v56
	v_mul_f32_e32 v44, v44, v121
	v_mul_f32_e32 v44, v44, v49
	v_mul_f32_e32 v49, v61, v59
	v_add_f32_e32 v59, 1.0, v60
	v_rcp_f32_e32 v59, v59
	v_exp_f32_e64 v60, -v54
	v_mul_f32_e32 v49, v49, v120
	v_mul_f32_e32 v49, v49, v45
	v_mul_f32_e32 v45, v56, v59
	v_add_f32_e32 v56, 1.0, v60
	v_rcp_f32_e32 v56, v56
	v_mul_f32_e32 v45, v45, v125
	v_mul_f32_e32 v45, v45, v50
	v_exp_f32_e64 v50, -v57
	v_mul_f32_e32 v54, v54, v56
	v_exp_f32_e64 v56, -v55
	v_mul_f32_e32 v54, v54, v124
	v_add_f32_e32 v50, 1.0, v50
	v_mul_f32_e32 v54, v54, v46
	v_add_f32_e32 v46, 1.0, v56
	v_rcp_f32_e32 v50, v50
	v_rcp_f32_e32 v46, v46
	v_lshl_add_u64 v[52:53], s[48:49], 0, v[52:53]
	v_lshl_add_u64 v[52:53], v[52:53], 0, v[66:67]
	v_mul_f32_e32 v50, v57, v50
	v_mul_f32_e32 v46, v55, v46
	v_mul_f32_e32 v50, v50, v175
	v_mul_f32_e32 v46, v46, v174
	v_mul_f32_e32 v50, v50, v51
	v_mul_f32_e32 v47, v46, v47
	v_cvt_pk_bf16_f32 v44, v48, v44
	v_cvt_pk_bf16_f32 v45, v45, v50
	v_cvt_pk_bf16_f32 v46, v58, v49
	v_cvt_pk_bf16_f32 v47, v54, v47
	global_store_dwordx4 v[52:53], v[44:47], off nt
	v_mov_b32_e32 v114, v110
	v_mov_b32_e32 v115, v111
	v_mul_f32_e32 v46, 0x3fb8aa3b, v209
	v_pk_mul_f32 v[50:51], v[40:41], v[46:47] op_sel_hi:[1,0]
	v_pk_mul_f32 v[52:53], v[36:37], v[46:47] op_sel_hi:[1,0]
	v_exp_f32_e64 v36, -v50
	v_exp_f32_e64 v55, -v52
	v_pk_mul_f32 v[48:49], v[42:43], v[46:47] op_sel_hi:[1,0]
	v_mfma_f32_16x16x32_bf16 v[40:43], v[104:107], v[92:95], 0
	v_add_f32_e32 v36, 1.0, v36
	v_rcp_f32_e32 v54, v36
	v_pk_mul_f32 v[46:47], v[38:39], v[46:47] op_sel_hi:[1,0]
	v_mfma_f32_16x16x32_bf16 v[36:39], v[114:117], v[92:95], 0
	v_lshlrev_b64 v[44:45], 14, v[172:173]
	v_mul_f32_e32 v50, v50, v54
	v_add_f32_e32 v54, 1.0, v55
	v_rcp_f32_e32 v54, v54
	v_exp_f32_e64 v55, -v51
	v_mul_f32_e32 v50, v50, v65
	v_mul_f32_e32 v40, v50, v40
	v_mul_f32_e32 v50, v52, v54
	v_add_f32_e32 v52, 1.0, v55
	v_rcp_f32_e32 v52, v52
	v_exp_f32_e64 v54, -v53
	v_mul_f32_e32 v50, v50, v64
	v_mul_f32_e32 v50, v50, v36
	v_mul_f32_e32 v36, v51, v52
	v_add_f32_e32 v51, 1.0, v54
	v_rcp_f32_e32 v51, v51
	v_exp_f32_e64 v52, -v48
	v_mul_f32_e32 v36, v36, v121
	v_mul_f32_e32 v36, v36, v41
	v_mul_f32_e32 v41, v53, v51
	v_add_f32_e32 v51, 1.0, v52
	v_rcp_f32_e32 v51, v51
	v_exp_f32_e64 v52, -v46
	v_mul_f32_e32 v41, v41, v120
	v_mul_f32_e32 v41, v41, v37
	v_mul_f32_e32 v37, v48, v51
	v_add_f32_e32 v48, 1.0, v52
	v_rcp_f32_e32 v48, v48
	v_mul_f32_e32 v37, v37, v125
	v_mul_f32_e32 v37, v37, v42
	v_exp_f32_e64 v42, -v49
	v_mul_f32_e32 v46, v46, v48
	v_exp_f32_e64 v48, -v47
	v_mul_f32_e32 v46, v46, v124
	v_add_f32_e32 v42, 1.0, v42
	v_mul_f32_e32 v46, v46, v38
	v_add_f32_e32 v38, 1.0, v48
	v_rcp_f32_e32 v42, v42
	v_rcp_f32_e32 v38, v38
	v_lshl_add_u64 v[44:45], s[48:49], 0, v[44:45]
	v_lshl_add_u64 v[44:45], v[44:45], 0, v[66:67]
	v_mul_f32_e32 v42, v49, v42
	v_mul_f32_e32 v38, v47, v38
	v_mul_f32_e32 v42, v42, v175
	v_mul_f32_e32 v38, v38, v174
	v_mul_f32_e32 v42, v42, v43
	v_mul_f32_e32 v39, v38, v39
	v_cvt_pk_bf16_f32 v36, v40, v36
	v_cvt_pk_bf16_f32 v37, v37, v42
	v_cvt_pk_bf16_f32 v38, v50, v41
	v_cvt_pk_bf16_f32 v39, v46, v39
	global_store_dwordx4 v[44:45], v[36:39], off nt
	v_mov_b32_e32 v84, v98
	v_mov_b32_e32 v85, v99
	v_mul_f32_e32 v38, 0x3fb8aa3b, v208
	v_pk_mul_f32 v[40:41], v[32:33], v[38:39] op_sel_hi:[1,0]
	v_lshlrev_b64 v[36:37], 14, v[170:171]
	v_exp_f32_e64 v39, -v40
	v_lshl_add_u64 v[36:37], s[48:49], 0, v[36:37]
	v_lshl_add_u64 v[36:37], v[36:37], 0, v[66:67]
	v_mov_b32_e32 v70, v90
	v_pk_mul_f32 v[44:45], v[28:29], v[38:39] op_sel_hi:[1,0]
	v_add_f32_e32 v28, 1.0, v39
	v_rcp_f32_e32 v46, v28
	v_exp_f32_e64 v47, -v44
	v_pk_mul_f32 v[42:43], v[34:35], v[38:39] op_sel_hi:[1,0]
	v_mfma_f32_16x16x32_bf16 v[32:35], v[100:103], v[92:95], 0
	v_mul_f32_e32 v40, v40, v46
	v_add_f32_e32 v46, 1.0, v47
	v_rcp_f32_e32 v46, v46
	v_exp_f32_e64 v47, -v41
	v_mul_f32_e32 v40, v40, v65
	s_nop 2
	v_mul_f32_e32 v32, v40, v32
	v_mul_f32_e32 v40, v44, v46
	v_add_f32_e32 v44, 1.0, v47
	v_pk_mul_f32 v[38:39], v[30:31], v[38:39] op_sel_hi:[1,0]
	s_waitcnt lgkmcnt(0)
	v_mfma_f32_16x16x32_bf16 v[28:31], v[96:99], v[92:95], 0
	v_rcp_f32_e32 v44, v44
	v_exp_f32_e64 v46, -v45
	v_mul_f32_e32 v40, v40, v64
	v_mov_b32_e32 v71, v91
	s_and_b64 vcc, exec, s[20:21]
	s_nop 2
	v_mul_f32_e32 v40, v40, v28
	v_mul_f32_e32 v28, v41, v44
	v_add_f32_e32 v41, 1.0, v46
	v_rcp_f32_e32 v41, v41
	v_exp_f32_e64 v44, -v42
	v_mul_f32_e32 v28, v28, v121
	v_mul_f32_e32 v28, v28, v33
	v_mul_f32_e32 v33, v45, v41
	v_add_f32_e32 v41, 1.0, v44
	v_rcp_f32_e32 v41, v41
	v_exp_f32_e64 v44, -v38
	v_mul_f32_e32 v33, v33, v120
	v_mul_f32_e32 v33, v33, v29
	v_mul_f32_e32 v29, v42, v41
	v_add_f32_e32 v41, 1.0, v44
	v_rcp_f32_e32 v41, v41
	v_mul_f32_e32 v29, v29, v125
	v_mul_f32_e32 v29, v29, v34
	v_exp_f32_e64 v34, -v43
	v_mul_f32_e32 v38, v38, v41
	v_exp_f32_e64 v41, -v39
	v_mul_f32_e32 v38, v38, v124
	v_add_f32_e32 v34, 1.0, v34
	v_mul_f32_e32 v38, v38, v30
	v_add_f32_e32 v30, 1.0, v41
	v_rcp_f32_e32 v34, v34
	v_rcp_f32_e32 v30, v30
	v_cvt_pk_bf16_f32 v28, v32, v28
	v_mul_f32_e32 v34, v43, v34
	v_mul_f32_e32 v30, v39, v30
	v_mul_f32_e32 v34, v34, v175
	v_mul_f32_e32 v30, v30, v174
	v_mul_f32_e32 v34, v34, v35
	v_mul_f32_e32 v31, v30, v31
	v_cvt_pk_bf16_f32 v29, v29, v34
	v_cvt_pk_bf16_f32 v30, v40, v33
	v_cvt_pk_bf16_f32 v31, v38, v31
	global_store_dwordx4 v[36:37], v[28:31], off nt
	s_nop 1
	v_mul_f32_e32 v30, 0x3fb8aa3b, v207
	v_pk_mul_f32 v[34:35], v[24:25], v[30:31] op_sel_hi:[1,0]
	v_pk_mul_f32 v[36:37], v[20:21], v[30:31] op_sel_hi:[1,0]
	v_exp_f32_e64 v20, -v34
	v_exp_f32_e64 v39, -v36
	v_pk_mul_f32 v[32:33], v[26:27], v[30:31] op_sel_hi:[1,0]
	v_mfma_f32_16x16x32_bf16 v[24:27], v[88:91], v[92:95], 0
	v_add_f32_e32 v20, 1.0, v20
	v_rcp_f32_e32 v38, v20
	v_pk_mul_f32 v[30:31], v[22:23], v[30:31] op_sel_hi:[1,0]
	v_mfma_f32_16x16x32_bf16 v[20:23], v[84:87], v[92:95], 0
	v_lshlrev_b64 v[28:29], 14, v[168:169]
	v_mul_f32_e32 v34, v34, v38
	v_add_f32_e32 v38, 1.0, v39
	v_rcp_f32_e32 v38, v38
	v_exp_f32_e64 v39, -v35
	v_mul_f32_e32 v34, v34, v65
	v_mul_f32_e32 v24, v34, v24
	v_mul_f32_e32 v34, v36, v38
	v_add_f32_e32 v36, 1.0, v39
	v_rcp_f32_e32 v36, v36
	v_exp_f32_e64 v38, -v37
	v_mul_f32_e32 v34, v34, v64
	v_mul_f32_e32 v34, v34, v20
	v_mul_f32_e32 v20, v35, v36
	v_add_f32_e32 v35, 1.0, v38
	v_rcp_f32_e32 v35, v35
	v_exp_f32_e64 v36, -v32
	v_mul_f32_e32 v20, v20, v121
	v_mul_f32_e32 v20, v20, v25
	v_mul_f32_e32 v25, v37, v35
	v_add_f32_e32 v35, 1.0, v36
	v_rcp_f32_e32 v35, v35
	v_exp_f32_e64 v36, -v30
	v_mul_f32_e32 v25, v25, v120
	v_mul_f32_e32 v25, v25, v21
	v_mul_f32_e32 v21, v32, v35
	v_add_f32_e32 v32, 1.0, v36
	v_rcp_f32_e32 v32, v32
	v_mul_f32_e32 v21, v21, v125
	v_mul_f32_e32 v21, v21, v26
	v_exp_f32_e64 v26, -v33
	v_mul_f32_e32 v30, v30, v32
	v_exp_f32_e64 v32, -v31
	v_mul_f32_e32 v30, v30, v124
	v_add_f32_e32 v26, 1.0, v26
	v_mul_f32_e32 v30, v30, v22
	v_add_f32_e32 v22, 1.0, v32
	v_rcp_f32_e32 v26, v26
	v_rcp_f32_e32 v22, v22
	v_lshl_add_u64 v[28:29], s[48:49], 0, v[28:29]
	v_lshl_add_u64 v[28:29], v[28:29], 0, v[66:67]
	v_mul_f32_e32 v26, v33, v26
	v_mul_f32_e32 v22, v31, v22
	v_mul_f32_e32 v26, v26, v175
	v_mul_f32_e32 v22, v22, v174
	v_mul_f32_e32 v26, v26, v27
	v_mul_f32_e32 v23, v22, v23
	v_cvt_pk_bf16_f32 v20, v24, v20
	v_cvt_pk_bf16_f32 v21, v21, v26
	v_cvt_pk_bf16_f32 v22, v34, v25
	v_cvt_pk_bf16_f32 v23, v30, v23
	global_store_dwordx4 v[28:29], v[20:23], off nt
	s_nop 1
	v_mul_f32_e32 v22, 0x3fb8aa3b, v206
	v_pk_mul_f32 v[26:27], v[16:17], v[22:23] op_sel_hi:[1,0]
	v_pk_mul_f32 v[28:29], v[12:13], v[22:23] op_sel_hi:[1,0]
	v_exp_f32_e64 v12, -v26
	v_exp_f32_e64 v31, -v28
	v_lshlrev_b64 v[20:21], 14, v[166:167]
	v_lshl_add_u64 v[20:21], s[48:49], 0, v[20:21]
	v_add_f32_e32 v12, 1.0, v12
	v_rcp_f32_e32 v30, v12
	v_lshl_add_u64 v[20:21], v[20:21], 0, v[66:67]
	v_pk_mul_f32 v[24:25], v[18:19], v[22:23] op_sel_hi:[1,0]
	v_mov_b32_e32 v66, v86
	v_mul_f32_e32 v26, v26, v30
	v_add_f32_e32 v30, 1.0, v31
	v_mov_b32_e32 v67, v87
	v_mfma_f32_16x16x32_bf16 v[16:19], v[70:73], v[92:95], 0
	v_rcp_f32_e32 v30, v30
	v_exp_f32_e64 v31, -v27
	v_mul_f32_e32 v26, v26, v65
	v_pk_mul_f32 v[22:23], v[14:15], v[22:23] op_sel_hi:[1,0]
	v_mfma_f32_16x16x32_bf16 v[12:15], v[66:69], v[92:95], 0
	s_nop 2
	v_mul_f32_e32 v16, v26, v16
	v_mul_f32_e32 v26, v28, v30
	v_add_f32_e32 v28, 1.0, v31
	v_rcp_f32_e32 v28, v28
	v_exp_f32_e64 v30, -v29
	v_mul_f32_e32 v26, v26, v64
	v_mul_f32_e32 v26, v26, v12
	v_mul_f32_e32 v12, v27, v28
	v_add_f32_e32 v27, 1.0, v30
	v_rcp_f32_e32 v27, v27
	v_exp_f32_e64 v28, -v24
	v_mul_f32_e32 v12, v12, v121
	v_mul_f32_e32 v12, v12, v17
	v_mul_f32_e32 v17, v29, v27
	v_add_f32_e32 v27, 1.0, v28
	v_rcp_f32_e32 v27, v27
	v_exp_f32_e64 v28, -v22
	v_mul_f32_e32 v17, v17, v120
	v_mul_f32_e32 v17, v17, v13
	v_mul_f32_e32 v13, v24, v27
	v_add_f32_e32 v24, 1.0, v28
	v_rcp_f32_e32 v24, v24
	v_mul_f32_e32 v13, v13, v125
	v_mul_f32_e32 v13, v13, v18
	v_exp_f32_e64 v18, -v25
	v_mul_f32_e32 v22, v22, v24
	v_exp_f32_e64 v24, -v23
	v_mul_f32_e32 v22, v22, v124
	v_mul_f32_e32 v22, v22, v14
	v_add_f32_e32 v18, 1.0, v18
	v_add_f32_e32 v14, 1.0, v24
	v_rcp_f32_e32 v14, v14
	v_rcp_f32_e32 v18, v18
	v_cvt_pk_bf16_f32 v12, v16, v12
	v_mul_f32_e32 v14, v23, v14
	v_mul_f32_e32 v18, v25, v18
	v_mul_f32_e32 v14, v14, v174
	v_mul_f32_e32 v18, v18, v175
	v_mul_f32_e32 v15, v14, v15
	v_mul_f32_e32 v18, v18, v19
	v_cvt_pk_bf16_f32 v13, v13, v18
	v_cvt_pk_bf16_f32 v14, v26, v17
	v_cvt_pk_bf16_f32 v15, v22, v15
	global_store_dwordx4 v[20:21], v[12:15], off nt
	s_cbranch_vccnz .LBB0_560
	v_mov_b32_e32 v74, v0
	v_mov_b32_e32 v75, v0
	v_mov_b32_e32 v78, v0
	v_mov_b32_e32 v79, v0
	v_lshl_add_u64 v[20:21], v[152:153], 0, s[56:57]
	v_mfma_f32_16x16x32_bf16 v[12:15], v[74:77], v[0:3], 0
	v_mfma_f32_16x16x32_bf16 v[16:19], v[78:81], v[0:3], 0
	v_lshl_add_u64 v[2:3], v[164:165], 1, v[20:21]
	v_mov_b32_e32 v20, v122
	v_mov_b32_e32 v21, v122
	s_nop 3
	v_pk_add_f32 v[14:15], v[20:21], v[14:15]
	v_pk_add_f32 v[12:13], v[122:123], v[12:13]
	v_pk_add_f32 v[18:19], v[20:21], v[18:19]
	v_pk_add_f32 v[16:17], v[122:123], v[16:17]
	v_cvt_pk_bf16_f32 v12, v12, v13
	v_cvt_pk_bf16_f32 v13, v14, v15
	s_nop 0
	v_cvt_pk_bf16_f32 v14, v16, v17
	v_cvt_pk_bf16_f32 v15, v18, v19
	global_store_dwordx4 v[2:3], v[12:15], off nt
.LBB0_560:
	s_nop 1
	v_mul_f32_e32 v12, 0x3fb8aa3b, v205
	v_pk_mul_f32 v[16:17], v[4:5], v[12:13] op_sel_hi:[1,0]
	v_pk_mul_f32 v[14:15], v[8:9], v[12:13] op_sel_hi:[1,0]
	v_exp_f32_e64 v1, -v16
	v_mov_b32_e32 v74, v72
	v_mov_b32_e32 v75, v73
	v_exp_f32_e64 v18, -v14
	v_add_f32_e32 v1, 1.0, v1
	v_rcp_f32_e32 v1, v1
	v_mov_b32_e32 v78, v68
	v_mov_b32_e32 v79, v69
	v_mfma_f32_16x16x32_bf16 v[2:5], v[74:77], v[92:95], 0
	v_mul_f32_e32 v1, v16, v1
	v_add_f32_e32 v16, 1.0, v18
	v_rcp_f32_e32 v16, v16
	v_exp_f32_e64 v18, -v17
	v_mul_f32_e32 v1, v1, v65
	s_nop 2
	v_mul_f32_e32 v1, v1, v2
	v_mul_f32_e32 v2, v14, v16
	v_add_f32_e32 v14, 1.0, v18
	v_pk_mul_f32 v[10:11], v[10:11], v[12:13] op_sel_hi:[1,0]
	v_pk_mul_f32 v[12:13], v[6:7], v[12:13] op_sel_hi:[1,0]
	v_mfma_f32_16x16x32_bf16 v[6:9], v[78:81], v[92:95], 0
	v_rcp_f32_e32 v14, v14
	v_exp_f32_e64 v16, -v15
	v_mul_f32_e32 v2, v2, v64
	s_andn2_b64 vcc, exec, s[18:19]
	s_mov_b64 s[18:19], -1
	s_nop 2
	v_mul_f32_e32 v6, v2, v6
	v_mul_f32_e32 v2, v17, v14
	v_add_f32_e32 v14, 1.0, v16
	v_rcp_f32_e32 v14, v14
	v_exp_f32_e64 v16, -v12
	v_mul_f32_e32 v2, v2, v121
	v_mul_f32_e32 v2, v2, v3
	v_mul_f32_e32 v3, v15, v14
	v_add_f32_e32 v14, 1.0, v16
	v_rcp_f32_e32 v14, v14
	v_exp_f32_e64 v15, -v10
	v_mul_f32_e32 v3, v3, v120
	v_mul_f32_e32 v7, v3, v7
	v_mul_f32_e32 v3, v12, v14
	v_add_f32_e32 v12, 1.0, v15
	v_rcp_f32_e32 v12, v12
	v_mul_f32_e32 v3, v3, v125
	v_mul_f32_e32 v3, v3, v4
	v_exp_f32_e64 v4, -v13
	v_mul_f32_e32 v10, v10, v12
	v_exp_f32_e64 v12, -v11
	v_mul_f32_e32 v10, v10, v124
	v_add_f32_e32 v4, 1.0, v4
	v_rcp_f32_e32 v4, v4
	v_mul_f32_e32 v8, v10, v8
	v_add_f32_e32 v10, 1.0, v12
	v_rcp_f32_e32 v10, v10
	v_mul_f32_e32 v4, v13, v4
	v_mul_f32_e32 v4, v4, v175
	v_mul_f32_e32 v4, v4, v5
	v_mul_f32_e32 v5, v11, v10
	v_cvt_pk_bf16_f32 v2, v1, v2
	v_cvt_pk_bf16_f32 v3, v3, v4
	v_cvt_pk_bf16_f32 v4, v6, v7
	v_lshlrev_b64 v[6:7], 14, v[162:163]
	v_mul_f32_e32 v5, v5, v174
	v_lshl_add_u64 v[6:7], s[48:49], 0, v[6:7]
	v_mul_f32_e32 v5, v5, v9
	v_lshl_add_u64 v[6:7], v[164:165], 1, v[6:7]
	v_cvt_pk_bf16_f32 v5, v8, v5
	global_store_dwordx4 v[6:7], v[2:5], off nt
	s_cbranch_vccnz .LBB0_520
	s_and_b64 vcc, exec, s[20:21]
	s_cbranch_vccnz .LBB0_519
	s_barrier
	s_branch .LBB0_519
